# P1+P5 epilogue row-scale prefetch one tile ahead; P2a unit slot rotation for balance
# speedup vs baseline: 1.0039x; 1.0011x over previous
; __device__ __forceinline__ unsigned lane_id_fresh() { unsigned m = ~0u; asm volatile("" : "+s"(m)); return __builtin_amdgcn_mbcnt_hi(m, __builtin_amdgcn_mbcnt_lo(m, 0u)); }
;     __device__ __forceinline__ unsigned voffA(int R, int C) const { return (unsigned)(R * lda + C) * 2u; }
;     __device__ __forceinline__ size_t hB() const { return (size_t)8 * 1024 * 2; }
;     int lane_ = (int)lane_id_fresh(); asm volatile("" : "+v"(lane_));
;     const int lane = lane_, tid = wid * 64 + lane, wr = wid >> 2, wc = wid & 3, fr = lane & 15, fq = lane >> 4;
;     const int nt = K / BK;
;     unsigned voffA[2], voffB[2];
; #pragma unroll
;     for (int i = 0; i < 2; ++i) { int R, C; stage_rc(tid * 16 + i * 8192, R, C); const int Rb = Epi::PERM ? ((R & ~31) + perm32(R & 31)) : R;
;         voffA[i] = g.voffA(R, C); voffB[i] = g.voffB(Rb, C); }
;     const size_t kstep = (size_t)(BK * 2);
;     const size_t hstepA = g.hA(), hstepB = g.hB();
;     const unsigned ldsw = (unsigned)wid * 1024u;
;     const int aoff = lds_byte(wr * 64 + fr, fq * 8), boff = lds_byte(wc * 32 + fr, fq * 8);
;     ...
;     Unit cur, nxt; int ui = 0;
;     if (!S.next(0, cur)) return;
;     f32x4 acc[2][2][4][2];
; #pragma unroll
;     for (int a = 0; a < 2; ++a)
; #pragma unroll
;         for (int b = 0; b < 2; ++b)
; #pragma unroll
;             for (int m = 0; m < 4; ++m)
; #pragma unroll
;                 for (int n = 0; n < 2; ++n) acc[a][b][m][n] = (f32x4){0.f, 0.f, 0.f, 0.f};
;     bf16x8 At[4][2], B0[2][2], B1[2][2];
;     const char* cA = g.a(cur); const char* cB = g.b(cur);
;     S.a_ready(cur);
;     PG8_STAGE(PG8_SB(0, 0), cB, voffB); PG8_STAGE(PG8_SB(0, 1), cB + hstepB, voffB); PG8_STAGE(PG8_SA(0, 0), cA, voffA); PG8_STAGE(PG8_SA(0, 1), cA + hstepA, voffA);
;     if (wr == 1) PG8_BAR;
;     PG8_WAIT_V(2); PG8_BAR;
;     PG8_STAGE(PG8_SB(1, 0), cB + kstep, voffB); PG8_STAGE(PG8_SA(1, 0), cA + kstep, voffA); PG8_STAGE(PG8_SB(1, 1), cB + hstepB + kstep, voffB);
;     PG8_WAIT_V(6); PG8_BAR;
; __global__ void __launch_bounds__(NWAVES * 64, 2) mk_fwd(Args args) {
;     ...
;         pg8::AddrStd g{xb, wint, 2048, 2048, 30, 0u}; pg8::StaticOrder S; S.init(T, 4096, G, (int)blockIdx.x, WGM_Q);
;         pg8::EpiB<0, 1, false, true> E{qkv, 1024, inv0, nullptr, 1024, (size_t)T * 1024, QSCALE};
;         pg8::gemm_phase<pg8::EpiB<0, 1, false, true>, pg8::StaticOrder, pg8::AddrStd, true>(lds, 2048, g, S, E, wave);
.LBB0_169:
	v_writelane_b32 v254, s38, 12
	s_lshr_b32 s5, s48, 8
	s_lshl_b32 s33, s49, 10
	v_writelane_b32 v254, s39, 13
	v_writelane_b32 v254, s48, 14
	s_lshl_b32 s48, s5, 6
	v_writelane_b32 v254, s5, 16
	s_lshl_b32 s5, s5, 13
	v_writelane_b32 v254, s5, 18
	s_lshl_b32 s5, s49, 5
	s_and_b32 s50, s5, 0x60
	s_lshr_b32 s5, s50, 3
	s_add_u32 s10, s94, 0xa400000
	v_writelane_b32 v254, s5, 19
	s_addc_u32 s11, s95, 0
	v_writelane_b32 v254, s10, 20
	v_cndmask_b32_e64 v0, 0, 1, s[8:9]
	s_add_u32 s84, s94, 0xe400000
	v_writelane_b32 v254, s11, 21
	v_cmp_ne_u32_e64 s[10:11], 1, v0
	s_addc_u32 s85, s95, 0
	s_andn2_b64 vcc, exec, s[8:9]
	v_writelane_b32 v254, s10, 22
	s_nop 1
	v_writelane_b32 v254, s11, 23
	s_cbranch_vccnz .LBB0_285
	v_lshl_add_u32 v0, v8, 4, s33
	v_ashrrev_i32_e32 v1, 31, v0
	v_lshrrev_b32_e32 v1, 22, v1
	v_add_u32_e32 v1, v0, v1
	v_ashrrev_i32_e32 v1, 10, v1
	v_mul_i32_i24_e32 v2, 0x400, v1
	v_sub_u32_e32 v2, v0, v2
	v_lshrrev_b32_e32 v3, 4, v2
	v_bitop3_b32 v2, v3, v2, 32 bitop3:0x6c
	v_ashrrev_i32_e32 v4, 31, v2
	v_lshrrev_b32_e32 v4, 26, v4
	v_lshlrev_b32_e32 v3, 3, v1
	v_add_u32_e32 v4, v2, v4
	v_and_b32_e32 v3, -16, v3
	v_ashrrev_i32_e32 v5, 6, v4
	v_and_b32_e32 v4, 0xc0, v4
	v_add_u32_e32 v3, v5, v3
	v_sub_u32_e32 v2, v2, v4
	v_mov_b32_e32 v4, 1
	v_lshlrev_b32_e32 v1, 5, v1
	v_ashrrev_i16_sdwa v2, v4, sext(v2) dst_sel:DWORD dst_unused:UNUSED_PAD src0_sel:DWORD src1_sel:BYTE_0
	v_lshlrev_b32_e32 v6, 1, v3
	v_lshrrev_b32_e32 v7, 2, v3
	v_and_b32_e32 v5, 3, v5
	s_mov_b32 s5, 0xfffe0
	v_and_b32_e32 v1, 32, v1
	v_bfe_i32 v2, v2, 0, 16
	v_and_b32_e32 v6, 24, v6
	v_and_b32_e32 v7, 4, v7
	v_and_or_b32 v5, v3, s5, v5
	v_or3_b32 v5, v5, v7, v6
	v_add_lshl_u32 v1, v1, v2, 1
	v_add_u32_e32 v0, 0x2000, v0
	v_lshl_add_u32 v128, v3, 12, v1
	v_lshl_add_u32 v130, v5, 12, v1
	v_ashrrev_i32_e32 v1, 31, v0
	v_lshrrev_b32_e32 v1, 22, v1
	v_add_u32_e32 v1, v0, v1
	v_ashrrev_i32_e32 v1, 10, v1
	v_mul_i32_i24_e32 v2, 0x400, v1
	v_sub_u32_e32 v0, v0, v2
	v_lshrrev_b32_e32 v2, 4, v0
	v_bitop3_b32 v0, v2, v0, 32 bitop3:0x6c
	v_ashrrev_i32_e32 v3, 31, v0
	v_lshrrev_b32_e32 v3, 26, v3
	v_lshlrev_b32_e32 v2, 3, v1
	v_add_u32_e32 v3, v0, v3
	v_and_b32_e32 v2, -16, v2
	v_ashrrev_i32_e32 v5, 6, v3
	v_and_b32_e32 v3, 0xffc0, v3
	v_add_u32_e32 v2, v5, v2
	v_sub_u32_e32 v0, v0, v3
	v_and_b32_e32 v5, 3, v5
	v_lshrrev_b16_e32 v3, 7, v0
	v_and_or_b32 v5, v2, s5, v5
	s_ashr_i32 s7, s6, 31
	s_ashr_i32 s5, s4, 31
	v_and_b32_e32 v3, 1, v3
	s_lshl_b64 s[8:9], s[6:7], 20
	s_lshl_b64 s[10:11], s[4:5], 20
	v_add_u16_e32 v0, v0, v3
	s_add_u32 s30, s24, s10
	v_lshlrev_b32_e32 v1, 5, v1
	v_ashrrev_i16_sdwa v0, v4, sext(v0) dst_sel:DWORD dst_unused:UNUSED_PAD src0_sel:DWORD src1_sel:BYTE_0
	v_lshlrev_b32_e32 v3, 1, v2
	v_lshrrev_b32_e32 v4, 2, v2
	s_addc_u32 s31, s25, s11
	s_add_i32 s38, s33, 0
	v_and_b32_e32 v1, 32, v1
	v_bfe_i32 v0, v0, 0, 16
	v_and_b32_e32 v3, 24, v3
	v_and_b32_e32 v4, 4, v4
	s_add_u32 s98, s94, 0x100000
	s_addc_u32 s99, s95, 0
	s_lshl_b32 s100, s6, 8
	s_add_i32 s100, s100, s48
	v_and_or_b32 v248, v8, 15, s100
	v_mov_b32_e32 v249, 0
	v_lshl_add_u64 v[248:249], v[248:249], 2, s[98:99]
	global_load_dword v240, v[248:249], off
	global_load_dword v241, v[248:249], off offset:64
	global_load_dword v242, v[248:249], off offset:128
	global_load_dword v243, v[248:249], off offset:192
	global_load_dword v244, v[248:249], off offset:512
	global_load_dword v245, v[248:249], off offset:576
	global_load_dword v246, v[248:249], off offset:640
	global_load_dword v247, v[248:249], off offset:704
	s_add_i32 m0, s38, 0x10000
	v_or3_b32 v3, v5, v4, v3
	v_add_lshl_u32 v0, v1, v0, 1
	global_load_lds_dwordx4 v130, s[30:31]
	s_add_i32 m0, s38, 0x12000
	v_lshl_add_u32 v134, v3, 12, v0
	s_add_u32 s10, s30, 0x80000
	global_load_lds_dwordx4 v134, s[30:31]
	s_addc_u32 s11, s31, 0
	s_add_i32 m0, s38, 0x14000
	v_lshl_add_u32 v132, v2, 12, v0
	global_load_lds_dwordx4 v130, s[10:11]
	s_add_i32 m0, s38, 0x16000
	v_mov_b32_e32 v131, 0
	global_load_lds_dwordx4 v134, s[10:11]
	v_readlane_b32 s10, v254, 20
	v_readlane_b32 s11, v254, 21
	s_add_u32 s28, s10, s8
	s_addc_u32 s29, s11, s9
	s_add_i32 s39, s38, 0x2000
	s_mov_b32 m0, s38
	s_add_u32 s8, s28, 0x80000
	global_load_lds_dwordx4 v128, s[28:29]
	s_mov_b32 m0, s39
	s_addc_u32 s9, s29, 0
	s_add_i32 s52, s38, 0x4000
	global_load_lds_dwordx4 v132, s[28:29]
	s_mov_b32 m0, s52
	s_add_i32 s53, s38, 0x6000
	global_load_lds_dwordx4 v128, s[8:9]
	s_mov_b32 m0, s53
	v_readlane_b32 s5, v254, 16
	global_load_lds_dwordx4 v132, s[8:9]
	v_mov_b32_e32 v135, v131
	v_mov_b32_e32 v129, v131
	v_mov_b32_e32 v133, v131
	s_cmp_eq_u32 s5, 1
	s_mov_b32 s54, 0
	v_lshl_add_u64 v[4:5], s[30:31], 0, v[130:131]
	v_lshl_add_u64 v[2:3], s[30:31], 0, v[134:135]
	v_lshl_add_u64 v[0:1], s[28:29], 0, v[128:129]
	s_cselect_b64 s[10:11], -1, 0
	s_cmp_lg_u32 s5, 1
	v_lshl_add_u64 v[6:7], s[28:29], 0, v[132:133]
	s_cbranch_scc1 .LBB0_172
	s_barrier

; __device__ __forceinline__ unsigned lane_id_fresh() { unsigned m = ~0u; asm volatile("" : "+s"(m)); return __builtin_amdgcn_mbcnt_hi(m, __builtin_amdgcn_mbcnt_lo(m, 0u)); }
;     __device__ __forceinline__ void operator()(const f32x4 (&acc)[2][2][4][2], const Unit& u, int wr, int wc, int fr, int fq) const {
;         { int l_ = (int)lane_id_fresh(); asm volatile("" : "+v"(l_)); fr = l_ & 15; fq = l_ >> 4; }
;         const int row0 = u.pm * BM + wr * 64 + fr; int colt = u.pn * BM; bf16_t* base = O;
;         float sc = 1.f; bool hm = false, k8 = false; if (split_cols) { const int t = colt / split_cols; base += (size_t)t * split_stride; colt -= t * split_cols; if (t == 0) sc = scale0; hm = HM && t < 3; k8 = HM && (t == 1 || t == 2); }
;         const int col0 = colt + wc * 32 + 8 * fq, gcol0 = u.pn * BM + wc * 32 + 8 * fq;
;         const size_t bstep = hm ? (size_t)4096 * 128 : (size_t)HALF;
;         f32x4 cv[2][2];
; #pragma unroll
;         for (int bj = 0; bj < 2; ++bj)
; #pragma unroll
;             for (int n = 0; n < 2; ++n) cv[bj][n] = CS ? *(const f32x4*)(cs + gcol0 + bj * HALF + 4 * n) : (f32x4){1.f, 1.f, 1.f, 1.f};
;         float rsv[2][4];
; #pragma unroll
;         for (int ai = 0; ai < 2; ++ai)
; #pragma unroll
;             for (int m = 0; m < 4; ++m) rsv[ai][m] = RS ? rs[row0 + ai * HALF + m * 16] : 1.0f;
; #pragma unroll
;         for (int ai = 0; ai < 2; ++ai)
; #pragma unroll
;             for (int m = 0; m < 4; ++m) { const int r = row0 + ai * HALF + m * 16;
;                 bf16_t* rowp = hm ? base + ((size_t)((r >> 12) * 8 + (colt >> 7)) * 4096 + (r & 4095)) * 128 + wc * 32 + 8 * fq : base + (size_t)r * ldc + col0;
.LBB0_185:
	s_mov_b32 s5, -1
	s_lshl_b32 s19, s4, 8
	v_mbcnt_lo_u32_b32 v130, s5, 0
	v_mbcnt_hi_u32_b32 v130, s5, v130
	s_lshl_b32 s5, s6, 8
	s_add_i32 s5, s5, s48
	s_ashr_i32 s6, s4, 31
	v_and_or_b32 v140, v130, 15, s5
	v_ashrrev_i32_e32 v141, 31, v140
	v_or_b32_e32 v152, 16, v140
	v_or_b32_e32 v150, 32, v140
	v_or_b32_e32 v146, 48, v140
	v_lshl_add_u64 v[142:143], v[140:141], 2, s[12:13]
	v_ashrrev_i32_e32 v153, 31, v152
	v_ashrrev_i32_e32 v151, 31, v150
	v_ashrrev_i32_e32 v147, 31, v146
	v_lshl_add_u64 v[144:145], v[152:153], 2, s[12:13]
	v_lshl_add_u64 v[148:149], v[150:151], 2, s[12:13]
	v_lshl_add_u64 v[154:155], v[146:147], 2, s[12:13]
	v_mov_b32_e32 v158, v240
	v_mov_b32_e32 v173, v241
	v_mov_b32_e32 v172, v242
	v_mov_b32_e32 v171, v243
	v_mov_b32_e32 v170, v244
	v_mov_b32_e32 v169, v245
	v_mov_b32_e32 v168, v246
	v_mov_b32_e32 v167, v247
	s_lshl_b32 s98, s20, 8
	s_add_i32 s98, s98, s48
	s_cmp_lg_u64 s[8:9], 0
	s_cselect_b32 s98, s98, s5
	v_and_or_b32 v248, v140, 15, s98
	v_mov_b32_e32 v249, 0
	v_lshl_add_u64 v[248:249], v[248:249], 2, s[12:13]
	global_load_dword v240, v[248:249], off
	global_load_dword v241, v[248:249], off offset:64
	global_load_dword v242, v[248:249], off offset:128
	global_load_dword v243, v[248:249], off offset:192
	global_load_dword v244, v[248:249], off offset:512
	global_load_dword v245, v[248:249], off offset:576
	global_load_dword v246, v[248:249], off offset:640
	global_load_dword v247, v[248:249], off offset:704
	s_lshr_b32 s6, s6, 30
	s_add_i32 s6, s4, s6
	s_ashr_i32 s36, s6, 2
	s_ashr_i32 s37, s36, 31
	s_lshl_b64 s[6:7], s[36:37], 25
	s_add_u32 s28, s84, s6
	s_addc_u32 s29, s85, s7
	s_lshl_b32 s6, s36, 10
	s_sub_i32 s19, s19, s6
	s_cmp_lt_i32 s4, 12
	s_cselect_b64 s[6:7], -1, 0
	s_cmp_gt_i32 s4, 11
	v_ashrrev_i32_e32 v130, 1, v130
	s_cselect_b64 s[30:31], -1, 0
	v_and_b32_e32 v156, -8, v130
	s_or_b32 s21, s19, s50
	v_add_u32_e32 v142, s21, v156
	s_add_u32 s34, s28, s50
	s_addc_u32 s35, s29, 0
	v_ashrrev_i32_e32 v143, 31, v142
	v_lshl_add_u64 v[142:143], v[142:143], 1, s[28:29]
	s_add_u32 s28, s34, s50
	s_addc_u32 s29, s35, 0
	s_mov_b64 s[40:41], -1
	s_and_b64 vcc, exec, s[30:31]
	v_lshlrev_b32_e32 v159, 7, v140
	s_cbranch_vccz .LBB0_187
	v_lshlrev_b64 v[144:145], 11, v[140:141]
	v_lshl_add_u64 v[154:155], v[142:143], 0, v[144:145]
	v_and_b32_e32 v130, 0x7e780, v159
	s_mov_b64 s[40:41], 0

;     __device__ __forceinline__ const char* a(const Unit& u) const { return (const char*)A + (size_t)u.pm * 2 * hA(); }
;     __device__ __forceinline__ const char* b(const Unit& u) const { return (const char*)Bt + (size_t)u.pn * 2 * hB() + (size_t)(u.pm >> gshift) * goff; }
;     __device__ __forceinline__ const char* a(const Unit& u) const { return (const char*)A + (size_t)u.pm * 2 * hA(); }
;     __device__ __forceinline__ const char* b(const Unit& u) const { return (const char*)Bt + (size_t)((u.pn >> 4) * 4096 + (u.pn & 15) * 16) * 1024 * 2 + (size_t)(u.pm >> 1) * 512; }
;     __device__ __forceinline__ const char* a(const Unit&) const { return (const char*)A; }
;     __device__ __forceinline__ const char* b(const Unit& u) const { return (const char*)Bt + ((size_t)(((u.pm >> 4) * 1024 + u.pn * 256) * 16 + (u.pm & 15)) * 512) * 2; }
;     __device__ __forceinline__ void operator()(const f32x4 (&acc)[2][2][4][2], const Unit& u, int wr, int wc, int fr, int fq) const {
;     ...
;             for (int m = 0; m < 4; ++m) { const int r = row0 + ai * HALF + m * 16;
;                 bf16_t* rowp = hm ? base + ((size_t)((r >> 12) * 8 + (colt >> 7)) * 4096 + (r & 4095)) * 128 + wc * 32 + 8 * fq : base + (size_t)r * ldc + col0;
;                 float rv = sc; if (RS == 1) rv *= rsv[ai][m]; if (RS == 2) rv *= __builtin_amdgcn_rsqf(rsv[ai][m] * (1.0f / DM) + EPS);
; #pragma unroll
;                 for (int bj = 0; bj < 2; ++bj) { f32x4 v0 = acc[ai][bj][m][0] * rv, v1 = acc[ai][bj][m][1] * rv;
;                     if (CS) { v0 = v0 * cv[bj][0]; v1 = v1 * cv[bj][1]; }
;                     if (ACT == 2) {
; #pragma unroll
;                         for (int e = 0; e < 4; ++e) { float a = v0[e] > 0.f ? v0[e] : 0.f, b = v1[e] > 0.f ? v1[e] : 0.f; v0[e] = a * a; v1[e] = b * b; } }
;                     if (k8) {
;                         u32x2 w8; w8.x = pk_fp8x4(v0); w8.y = pk_fp8x4(v1);
;                         *(u32x2*)((unsigned char*)base + ((size_t)((r >> 12) * 8 + (colt >> 7) + bj) * 4096 + (r & 4095)) * 128 + wc * 32 + 8 * fq) = w8;
;                     } else {
;                     u32x4 w; w.x = cvt_pk_bf16(v0[0], v0[1]); w.y = cvt_pk_bf16(v0[2], v0[3]); w.z = cvt_pk_bf16(v1[0], v1[1]); w.w = cvt_pk_bf16(v1[2], v1[3]);
;                     *(u32x4*)(rowp + bj * bstep) = w; } } }
.LBB0_189:
	s_add_i32 s4, s4, 3
	s_cmp_lt_u32 s4, 7
	s_cselect_b64 vcc, -1, 0
	s_add_i32 s4, s36, -1
	v_cndmask_b32_e32 v141, 1.0, v165, vcc
	s_cmp_gt_u32 s4, 1
	s_cselect_b64 s[36:37], -1, 0
	v_mul_f32_e32 v158, v141, v158
	v_pk_mul_f32 v[126:127], v[126:127], v[158:159] op_sel_hi:[1,0]
	v_pk_mul_f32 v[160:161], v[124:125], v[158:159] op_sel_hi:[1,0]
	v_pk_mul_f32 v[124:125], v[122:123], v[158:159] op_sel_hi:[1,0]
	v_pk_mul_f32 v[162:163], v[120:121], v[158:159] op_sel_hi:[1,0]
	s_mov_b64 s[4:5], -1
	s_and_b64 vcc, exec, s[36:37]
	s_cbranch_vccz .LBB0_191
	v_cvt_pk_bf16_f32 v120, v160, v161
	v_cvt_pk_bf16_f32 v121, v126, v127
	v_cvt_pk_bf16_f32 v122, v162, v163
	v_cvt_pk_bf16_f32 v123, v124, v125
	global_store_dwordx4 v[154:155], v[120:123], off
	s_mov_b64 s[4:5], 0

; __global__ void __launch_bounds__(NWAVES * 64, 2) mk_fwd(Args args) {
;     ...
;         int U = vwave;
;         if (U < NU) {
;             const bf16_t *cq, *ck, *cv, *nq, *nk, *nv; bf16_t *cp, *np_; float *cm, *nm; int ctq, cdl, ntq = 0, ndl = 1; float csl, nsl = 0.f;
;             AT_DEC_AB(U, cq, ck, cv, ctq, cdl, csl, cp, cm);
;             nq = cq; nk = ck; nv = cv; np_ = cp; nm = cm;
;             bf16x8 qr[8];
;             at_unit_prologue(wl, qr, cq, ck, cv, ctq, cdl, lna);
; #pragma unroll 1
;             for (;;) {
;                 const int Un = U + NGW; const bool hn = Un < NU;
;                 if (hn) AT_DEC_AB(Un, nq, nk, nv, ntq, ndl, nsl, np_, nm);
;                 attn_unit(false, hn, wl, cq, ck, cv, ctq, cdl, csl, qr, nq, nk, nv, ntq, ndl, cp, cm, nullptr, nullptr, nullptr, nullptr, nullptr, lna);
;                 if (!hn) break;
;                 U = Un; cq = nq; ck = nk; cv = nv; ctq = ntq; cdl = ndl; csl = nsl; cp = np_; cm = nm;
.LBB0_366:
	s_add_i32 s91, s91, s96
	s_cmpk_lt_i32 s91, 0x2000
	s_cselect_b64 s[46:47], -1, 0
	s_cmpk_gt_i32 s91, 0x1fff
	s_cbranch_scc1 .LBB0_373
	s_lshr_b32 s6, s91, 11
	s_lshl_b32 s6, s6, 6
	s_add_i32 s6, s6, s91
	s_and_b32 s6, s6, 0xff
	s_lshl_b32 s10, s6, 5
	s_cmpk_gt_u32 s6, 0x7f
	s_cbranch_scc0 .LBB0_370
	s_add_i32 s6, s10, 0x7ffff000
	s_and_b32 s6, s6, 0x7fffff80
	s_or_b32 s67, s6, s87
	s_mov_b64 s[6:7], s[0:1]
	s_cbranch_execz .LBB0_371
	s_mov_b32 s39, 4
	s_mov_b64 s[8:9], 0x4100000
	s_branch .LBB0_372
